# v13 + P0 adaLN partial sums: 8 k per dependent round instead of 2 (32 -> 8 load rounds per item), same FMA order
# speedup vs baseline: 1.0093x; 1.0093x over previous
; __device__ __forceinline__ void phase0(const P0Args& A, LAS unsigned char* lds, int gw, int NGW, int wave, int lane, int gt, int NGT) {
;     ...
;             const int ks = r / 96, cb = r % 96, col = cb * 64 + lane;
;             float acc[8];
; #pragma unroll
;             for (int b = 0; b < 8; ++b) acc[b] = 0.f;
;             for (int kk = 0; kk < 64; ++kk) {
;                 const int k = ks * 64 + kk; const float w = A.ada_w[(size_t)k * ADAW + col];
; #pragma unroll
;                 for (int b = 0; b < 8; ++b) acc[b] += A.c[b * D + k] * w;
;             }
;             float* adap = (float*)(A.ws + WS_ADAP);
; #pragma unroll
;             for (int b = 0; b < 8; ++b) adap[(size_t)(ks * 8 + b) * ADAW + col] = acc[b];
;             continue;
.LBB0_61:
	s_mul_hi_i32 s6, s41, 0x2aaaaaab
	s_lshr_b32 s8, s6, 31
	s_ashr_i32 s6, s6, 4
	s_add_i32 s6, s6, s8
	s_mul_i32 s8, s6, 0x60
	s_sub_i32 s8, s41, s8
	v_lshl_add_u32 v46, s8, 6, v62
	s_lshl_b32 s8, s6, 6
	s_ashr_i32 s9, s8, 31
	s_mul_i32 s10, s6, 0x180000
	s_mul_hi_i32 s11, s8, 0x6000
	s_add_u32 s10, s54, s10
	s_addc_u32 s11, s55, s11
	s_lshl_b64 s[8:9], s[8:9], 2
	v_ashrrev_i32_e32 v47, 31, v46
	s_add_u32 s8, s50, s8
	v_mov_b32_e32 v44, 0
	v_lshl_add_u64 v[50:51], v[46:47], 2, s[10:11]
	s_addc_u32 s9, s51, s9
	s_mov_b64 s[24:25], 0
	v_mov_b32_e32 v45, v44
	v_mov_b32_e32 v54, v44
	v_mov_b32_e32 v55, v44
	v_mov_b32_e32 v52, v44
	v_mov_b32_e32 v53, v44
	v_mov_b32_e32 v48, v44
	v_mov_b32_e32 v49, v44
	s_mov_b32 s98, s40
	s_mov_b32 s99, 0
.LBB0_62:
	s_add_u32 s10, s8, s24
	s_addc_u32 s11, s9, s25
	global_load_dword v124, v[50:51], off
	v_lshl_add_u64 v[50:51], v[50:51], 0, s[98:99]
	global_load_dword v125, v[50:51], off
	v_lshl_add_u64 v[50:51], v[50:51], 0, s[98:99]
	global_load_dword v126, v[50:51], off
	v_lshl_add_u64 v[50:51], v[50:51], 0, s[98:99]
	global_load_dword v127, v[50:51], off
	v_lshl_add_u64 v[50:51], v[50:51], 0, s[98:99]
	global_load_dword v128, v[50:51], off
	v_lshl_add_u64 v[50:51], v[50:51], 0, s[98:99]
	global_load_dword v129, v[50:51], off
	v_lshl_add_u64 v[50:51], v[50:51], 0, s[98:99]
	global_load_dword v130, v[50:51], off
	v_lshl_add_u64 v[50:51], v[50:51], 0, s[98:99]
	global_load_dword v131, v[50:51], off
	v_lshl_add_u64 v[50:51], v[50:51], 0, s[98:99]
	global_load_dwordx4 v[132:135], v3, s[10:11]
	global_load_dwordx4 v[136:139], v68, s[10:11]
	global_load_dwordx4 v[140:143], v69, s[10:11]
	global_load_dwordx4 v[144:147], v70, s[10:11]
	global_load_dwordx4 v[148:151], v71, s[10:11]
	global_load_dwordx4 v[152:155], v72, s[10:11]
	global_load_dwordx4 v[156:159], v73, s[10:11]
	global_load_dwordx4 v[160:163], v74, s[10:11]
	global_load_dwordx4 v[164:167], v3, s[10:11] offset:16
	global_load_dwordx4 v[168:171], v68, s[10:11] offset:16
	global_load_dwordx4 v[172:175], v69, s[10:11] offset:16
	global_load_dwordx4 v[176:179], v70, s[10:11] offset:16
	global_load_dwordx4 v[180:183], v71, s[10:11] offset:16
	global_load_dwordx4 v[184:187], v72, s[10:11] offset:16
	global_load_dwordx4 v[188:191], v73, s[10:11] offset:16
	global_load_dwordx4 v[192:195], v74, s[10:11] offset:16
	s_add_u32 s24, s24, 32
	s_addc_u32 s25, s25, 0
	s_cmpk_eq_i32 s24, 0x100
	s_waitcnt vmcnt(8)
	v_fma_f32 v54, v124, v132, v54
	v_fma_f32 v55, v124, v136, v55
	v_fma_f32 v52, v124, v140, v52
	v_fma_f32 v53, v124, v144, v53
	v_fma_f32 v48, v124, v148, v48
	v_fma_f32 v49, v124, v152, v49
	v_fma_f32 v44, v124, v156, v44
	v_fma_f32 v45, v124, v160, v45
	v_fma_f32 v54, v125, v133, v54
	v_fma_f32 v55, v125, v137, v55
	v_fma_f32 v52, v125, v141, v52
	v_fma_f32 v53, v125, v145, v53
	v_fma_f32 v48, v125, v149, v48
	v_fma_f32 v49, v125, v153, v49
	v_fma_f32 v44, v125, v157, v44
	v_fma_f32 v45, v125, v161, v45
	v_fma_f32 v54, v126, v134, v54
	v_fma_f32 v55, v126, v138, v55
	v_fma_f32 v52, v126, v142, v52
	v_fma_f32 v53, v126, v146, v53
	v_fma_f32 v48, v126, v150, v48
	v_fma_f32 v49, v126, v154, v49
	v_fma_f32 v44, v126, v158, v44
	v_fma_f32 v45, v126, v162, v45
	v_fma_f32 v54, v127, v135, v54
	v_fma_f32 v55, v127, v139, v55
	v_fma_f32 v52, v127, v143, v52
	v_fma_f32 v53, v127, v147, v53
	v_fma_f32 v48, v127, v151, v48
	v_fma_f32 v49, v127, v155, v49
	v_fma_f32 v44, v127, v159, v44
	v_fma_f32 v45, v127, v163, v45
	s_waitcnt vmcnt(0)
	v_fma_f32 v54, v128, v164, v54
	v_fma_f32 v55, v128, v168, v55
	v_fma_f32 v52, v128, v172, v52
	v_fma_f32 v53, v128, v176, v53
	v_fma_f32 v48, v128, v180, v48
	v_fma_f32 v49, v128, v184, v49
	v_fma_f32 v44, v128, v188, v44
	v_fma_f32 v45, v128, v192, v45
	v_fma_f32 v54, v129, v165, v54
	v_fma_f32 v55, v129, v169, v55
	v_fma_f32 v52, v129, v173, v52
	v_fma_f32 v53, v129, v177, v53
	v_fma_f32 v48, v129, v181, v48
	v_fma_f32 v49, v129, v185, v49
	v_fma_f32 v44, v129, v189, v44
	v_fma_f32 v45, v129, v193, v45
	v_fma_f32 v54, v130, v166, v54
	v_fma_f32 v55, v130, v170, v55
	v_fma_f32 v52, v130, v174, v52
	v_fma_f32 v53, v130, v178, v53
	v_fma_f32 v48, v130, v182, v48
	v_fma_f32 v49, v130, v186, v49
	v_fma_f32 v44, v130, v190, v44
	v_fma_f32 v45, v130, v194, v45
	v_fma_f32 v54, v131, v167, v54
	v_fma_f32 v55, v131, v171, v55
	v_fma_f32 v52, v131, v175, v52
	v_fma_f32 v53, v131, v179, v53
	v_fma_f32 v48, v131, v183, v48
	v_fma_f32 v49, v131, v187, v49
	v_fma_f32 v44, v131, v191, v44
	v_fma_f32 v45, v131, v195, v45
	s_cbranch_scc0 .LBB0_62
	s_lshl_b32 s6, s6, 3
	v_lshl_add_u64 v[46:47], v[46:47], 2, s[4:5]
	v_mad_i64_i32 v[50:51], s[8:9], s6, v73, v[46:47]
	s_or_b32 s8, s6, 1
	global_store_dword v[50:51], v54, off
	v_mad_i64_i32 v[50:51], s[8:9], s8, v73, v[46:47]
	s_or_b32 s8, s6, 2
	global_store_dword v[50:51], v55, off
	v_mad_i64_i32 v[50:51], s[8:9], s8, v73, v[46:47]
	s_or_b32 s8, s6, 3
	global_store_dword v[50:51], v52, off
	v_mad_i64_i32 v[50:51], s[8:9], s8, v73, v[46:47]
	s_or_b32 s8, s6, 4
	global_store_dword v[50:51], v53, off
	v_mad_i64_i32 v[50:51], s[8:9], s8, v73, v[46:47]
	s_or_b32 s8, s6, 5
	global_store_dword v[50:51], v48, off
	v_mad_i64_i32 v[50:51], s[8:9], s8, v73, v[46:47]
	s_or_b32 s8, s6, 6
	s_or_b32 s6, s6, 7
	global_store_dword v[50:51], v49, off
	v_mad_i64_i32 v[48:49], s[8:9], s8, v73, v[46:47]
	v_mad_i64_i32 v[46:47], s[8:9], s6, v73, v[46:47]
	global_store_dword v[48:49], v44, off
	global_store_dword v[46:47], v45, off
	s_branch .LBB0_19
